# combo2
# speedup vs baseline: 1.0274x; 1.0204x over previous
.LBB0_934:
	s_mov_b64 s[6:7], 0
	s_andn2_b64 vcc, exec, s[8:9]
	v_readlane_b32 s12, v255, 26
	s_cbranch_vccnz .LBB0_971
	s_waitcnt vmcnt(0)
	v_readlane_b32 s4, v255, 26
	s_add_i32 s12, s4, 1
	s_waitcnt lgkmcnt(0)
	s_barrier
	s_mov_b64 s[4:5], exec
	v_readlane_b32 s6, v253, 57
	v_readlane_b32 s7, v253, 58
	s_and_b64 s[6:7], s[4:5], s[6:7]
	s_mov_b64 exec, s[6:7]
	s_cbranch_execz .LBB0_984
	s_mov_b64 s[6:7], exec
	v_mbcnt_lo_u32_b32 v0, s6, 0
	v_mbcnt_hi_u32_b32 v0, s7, v0
	v_cmp_eq_u32_e32 vcc, 0, v0
	buffer_wbl2 sc1
	s_waitcnt vmcnt(0)
	s_and_saveexec_b64 s[8:9], vcc
	s_cbranch_execz .LBB0_938
	s_bcnt1_i32_b64 s6, s[6:7]
	v_mov_b32_e32 v2, s6
	v_readlane_b32 s6, v254, 35
	v_readlane_b32 s7, v254, 36
	s_nop 4
	global_atomic_add v2, v1, v2, s[6:7] sc0
.LBB0_938:
	s_or_b64 exec, exec, s[8:9]
	s_waitcnt vmcnt(0)
	v_readfirstlane_b32 s6, v2
	s_nop 1
	v_add3_u32 v0, s6, v0, 1
	v_readlane_b32 s6, v254, 33
	s_mul_i32 s6, s12, s6
	s_nop 0
	v_cmp_eq_u32_e32 vcc, s6, v0
	s_and_saveexec_b64 s[6:7], vcc
	s_cbranch_execz .LBB0_958
	s_mov_b64 s[8:9], exec
	v_mbcnt_lo_u32_b32 v0, s8, 0
	v_mbcnt_hi_u32_b32 v0, s9, v0
	v_cmp_eq_u32_e32 vcc, 0, v0
	s_and_saveexec_b64 s[10:11], vcc
	s_cbranch_execz .LBB0_941
	s_bcnt1_i32_b64 s8, s[8:9]
	v_mov_b32_e32 v2, s8
	v_readlane_b32 s8, v254, 38
	v_readlane_b32 s9, v254, 39
	s_nop 4
	global_atomic_add v2, v1, v2, s[8:9] sc0
.LBB0_941:
	s_or_b64 exec, exec, s[10:11]
	s_waitcnt vmcnt(0)
	v_readfirstlane_b32 s8, v2
	s_nop 1
	v_add3_u32 v0, s8, v0, 1
	v_readlane_b32 s8, v254, 37
	s_mul_i32 s8, s12, s8
	s_nop 0
	v_cmp_eq_u32_e32 vcc, s8, v0
	s_and_b64 exec, exec, vcc
	s_cbranch_execz .LBB0_958
	s_mov_b64 s[8:9], exec
	v_mbcnt_lo_u32_b32 v0, s8, 0
	v_mbcnt_hi_u32_b32 v0, s9, v0
	v_cmp_eq_u32_e32 vcc, 0, v0
	s_and_saveexec_b64 s[10:11], vcc
	s_cbranch_execz .LBB0_944
	s_bcnt1_i32_b64 s8, s[8:9]
	v_mov_b32_e32 v0, s8
	v_readlane_b32 s8, v254, 40
	v_readlane_b32 s9, v254, 41
	s_nop 4
	global_atomic_add v1, v0, s[8:9]

.LBB0_982:
	s_or_b64 exec, exec, s[4:5]
	s_barrier
	v_readlane_b32 s12, v255, 26
	s_cbranch_execz .LBB0_1
	s_branch .LBB0_986
.LBB0_983:
	buffer_inv sc1
.LBB0_984:
	s_or_b64 exec, exec, s[4:5]
	s_mov_b64 s[6:7], -1
	s_barrier
